# v35 + touches for the 8th residual row pair, and an L2-prefetch touch loop over each wave's K slice before the sample-row GEMM K loop of the out-proj/FFN-out phases
# baseline (speedup 1.0000x reference)
.LBB0_1179:
	s_add_i32 s92, s42, 2
	s_add_u32 s72, s36, 0x80
	s_addc_u32 s43, s37, 0
	s_add_i32 s93, 0, 0x10000
	v_add_u32_e32 v1, s93, v223
	ds_read_b128 v[50:53], v1
	ds_read_b128 v[54:57], v1 offset:1024
	ds_read_b128 v[58:61], v1 offset:2048
	ds_read_b128 v[62:65], v1 offset:3072
	s_cmp_eq_u32 s88, s42
	s_cselect_b32 s42, s66, s72
	s_cselect_b32 s43, s67, s43
	s_cselect_b32 s73, s71, s91
	s_cselect_b32 s72, s70, s27
	v_lshl_add_u64 v[178:179], s[36:37], 0, v[206:207]
	s_add_i32 m0, s79, 0xc000
	ds_read_b128 v[66:69], v230
	ds_read_b128 v[70:73], v230 offset:1024
	ds_read_b128 v[74:77], v230 offset:2048
	ds_read_b128 v[78:81], v230 offset:3072
	ds_read_b128 v[146:149], v230 offset:4096
	ds_read_b128 v[154:157], v230 offset:5120
	ds_read_b128 v[170:173], v230 offset:6144
	ds_read_b128 v[174:177], v230 offset:7168
	global_load_lds_dwordx4 v[178:179], off
	v_lshl_add_u64 v[178:179], s[36:37], 0, v[204:205]
	s_add_i32 m0, s79, 0xe000
	s_nop 0
	global_load_lds_dwordx4 v[178:179], off
	s_waitcnt lgkmcnt(8)
	s_barrier
	s_waitcnt lgkmcnt(0)
	s_waitcnt lgkmcnt(0)
	v_mfma_f32_16x16x32_bf16 v[166:169], v[50:53], v[66:69], v[166:169]
	v_mfma_f32_16x16x32_bf16 v[162:165], v[58:61], v[66:69], v[162:165]
	v_mfma_f32_16x16x32_bf16 v[142:145], v[50:53], v[74:77], v[142:145]
	v_mfma_f32_16x16x32_bf16 v[138:141], v[58:61], v[74:77], v[138:141]
	v_mfma_f32_16x16x32_bf16 v[126:129], v[50:53], v[146:149], v[126:129]
	v_mfma_f32_16x16x32_bf16 v[122:125], v[58:61], v[146:149], v[122:125]
	v_mfma_f32_16x16x32_bf16 v[110:113], v[50:53], v[170:173], v[110:113]
	v_mfma_f32_16x16x32_bf16 v[106:109], v[58:61], v[170:173], v[106:109]
	v_mfma_f32_16x16x32_bf16 v[166:169], v[54:57], v[70:73], v[166:169]
	v_mfma_f32_16x16x32_bf16 v[162:165], v[62:65], v[70:73], v[162:165]
	v_mfma_f32_16x16x32_bf16 v[142:145], v[54:57], v[78:81], v[142:145]
	v_mfma_f32_16x16x32_bf16 v[138:141], v[62:65], v[78:81], v[138:141]
	v_mfma_f32_16x16x32_bf16 v[126:129], v[54:57], v[154:157], v[126:129]
	v_mfma_f32_16x16x32_bf16 v[122:125], v[62:65], v[154:157], v[122:125]
	v_mfma_f32_16x16x32_bf16 v[110:113], v[54:57], v[174:177], v[110:113]
	v_mfma_f32_16x16x32_bf16 v[106:109], v[62:65], v[174:177], v[106:109]
	s_barrier
	s_add_i32 s94, 0, 0x14000
	s_add_i32 s93, s93, s78
	v_add_u32_e32 v1, s94, v223
	v_lshl_add_u64 v[214:215], s[72:73], 0, v[202:203]
	s_mov_b32 m0, s93
	ds_read_b128 v[178:181], v1
	ds_read_b128 v[182:185], v1 offset:1024
	ds_read_b128 v[186:189], v1 offset:2048
	ds_read_b128 v[190:193], v1 offset:3072
	global_load_lds_dwordx4 v[214:215], off
	v_lshl_add_u64 v[236:237], s[72:73], 0, v[200:201]
	s_add_i32 m0, s93, 0x2000
	s_nop 0
	global_load_lds_dwordx4 v[236:237], off
	s_barrier
	s_waitcnt lgkmcnt(0)
	s_waitcnt lgkmcnt(0)
	v_mfma_f32_16x16x32_bf16 v[158:161], v[178:181], v[66:69], v[158:161]
	v_mfma_f32_16x16x32_bf16 v[66:69], v[186:189], v[66:69], v[150:153]
	v_mfma_f32_16x16x32_bf16 v[158:161], v[182:185], v[70:73], v[158:161]
	v_mfma_f32_16x16x32_bf16 v[66:69], v[190:193], v[70:73], v[66:69]
	v_mfma_f32_16x16x32_bf16 v[70:73], v[178:181], v[74:77], v[134:137]
	v_mfma_f32_16x16x32_bf16 v[74:77], v[186:189], v[74:77], v[130:133]
	v_mfma_f32_16x16x32_bf16 v[114:117], v[186:189], v[146:149], v[114:117]
	v_mfma_f32_16x16x32_bf16 v[102:105], v[178:181], v[170:173], v[102:105]
	v_mfma_f32_16x16x32_bf16 v[98:101], v[186:189], v[170:173], v[98:101]
	v_mfma_f32_16x16x32_bf16 v[70:73], v[182:185], v[78:81], v[70:73]
	v_mfma_f32_16x16x32_bf16 v[74:77], v[190:193], v[78:81], v[74:77]
	v_mfma_f32_16x16x32_bf16 v[78:81], v[178:181], v[146:149], v[118:121]
	v_mfma_f32_16x16x32_bf16 v[114:117], v[190:193], v[154:157], v[114:117]
	v_mfma_f32_16x16x32_bf16 v[102:105], v[182:185], v[174:177], v[102:105]
	v_mfma_f32_16x16x32_bf16 v[98:101], v[190:193], v[174:177], v[98:101]
	v_mfma_f32_16x16x32_bf16 v[78:81], v[182:185], v[154:157], v[78:81]
	s_mov_b32 m0, s79
	v_lshl_add_u64 v[238:239], s[42:43], 0, v[202:203]
	s_barrier
	ds_read_b128 v[118:121], v230 offset:16384
	ds_read_b128 v[130:133], v230 offset:17408
	ds_read_b128 v[134:137], v230 offset:18432
	ds_read_b128 v[146:149], v230 offset:19456
	ds_read_b128 v[150:153], v230 offset:20480
	ds_read_b128 v[154:157], v230 offset:21504
	ds_read_b128 v[170:173], v230 offset:22528
	ds_read_b128 v[174:177], v230 offset:23552
	global_load_lds_dwordx4 v[238:239], off
	v_lshl_add_u64 v[240:241], s[42:43], 0, v[200:201]
	s_mov_b32 m0, s80
	s_nop 0
	global_load_lds_dwordx4 v[240:241], off
	s_barrier
	s_waitcnt lgkmcnt(0)
	s_waitcnt lgkmcnt(0)
	v_mfma_f32_16x16x32_bf16 v[94:97], v[50:53], v[118:121], v[94:97]
	v_mfma_f32_16x16x32_bf16 v[90:93], v[58:61], v[118:121], v[90:93]
	v_mfma_f32_16x16x32_bf16 v[46:49], v[50:53], v[134:137], v[46:49]
	v_mfma_f32_16x16x32_bf16 v[42:45], v[58:61], v[134:137], v[42:45]
	v_mfma_f32_16x16x32_bf16 v[30:33], v[50:53], v[150:153], v[30:33]
	v_mfma_f32_16x16x32_bf16 v[26:29], v[58:61], v[150:153], v[26:29]
	v_mfma_f32_16x16x32_bf16 v[14:17], v[50:53], v[170:173], v[14:17]
	v_mfma_f32_16x16x32_bf16 v[10:13], v[58:61], v[170:173], v[10:13]
	v_mfma_f32_16x16x32_bf16 v[94:97], v[54:57], v[130:133], v[94:97]
	v_mfma_f32_16x16x32_bf16 v[90:93], v[62:65], v[130:133], v[90:93]
	v_mfma_f32_16x16x32_bf16 v[46:49], v[54:57], v[146:149], v[46:49]
	v_mfma_f32_16x16x32_bf16 v[42:45], v[62:65], v[146:149], v[42:45]
	v_mfma_f32_16x16x32_bf16 v[30:33], v[54:57], v[154:157], v[30:33]
	v_mfma_f32_16x16x32_bf16 v[26:29], v[62:65], v[154:157], v[26:29]
	v_mfma_f32_16x16x32_bf16 v[14:17], v[54:57], v[174:177], v[14:17]
	v_mfma_f32_16x16x32_bf16 v[10:13], v[62:65], v[174:177], v[10:13]
	s_barrier
	s_add_u32 s72, s72, s4
	s_addc_u32 s73, s73, 0
	s_add_i32 s93, s94, s78
	v_lshl_add_u64 v[242:243], s[72:73], 0, v[202:203]
	s_mov_b32 m0, s93
	v_lshl_add_u64 v[244:245], s[72:73], 0, v[200:201]
	global_load_lds_dwordx4 v[242:243], off
	s_add_i32 m0, s93, 0x2000
	s_nop 0
	global_load_lds_dwordx4 v[244:245], off
	s_waitcnt vmcnt(6)
	s_barrier
	v_mfma_f32_16x16x32_bf16 v[38:41], v[178:181], v[134:137], v[38:41]
	v_mfma_f32_16x16x32_bf16 v[34:37], v[186:189], v[134:137], v[34:37]
	v_mfma_f32_16x16x32_bf16 v[22:25], v[178:181], v[150:153], v[22:25]
	v_mfma_f32_16x16x32_bf16 v[18:21], v[186:189], v[150:153], v[18:21]
	v_mfma_f32_16x16x32_bf16 v[6:9], v[178:181], v[170:173], v[6:9]
	v_mfma_f32_16x16x32_bf16 v[2:5], v[186:189], v[170:173], v[2:5]
	v_mfma_f32_16x16x32_bf16 v[50:53], v[178:181], v[118:121], v[86:89]
	v_mfma_f32_16x16x32_bf16 v[54:57], v[186:189], v[118:121], v[82:85]
	v_mfma_f32_16x16x32_bf16 v[38:41], v[182:185], v[146:149], v[38:41]
	v_mfma_f32_16x16x32_bf16 v[34:37], v[190:193], v[146:149], v[34:37]
	v_mfma_f32_16x16x32_bf16 v[22:25], v[182:185], v[154:157], v[22:25]
	v_mfma_f32_16x16x32_bf16 v[18:21], v[190:193], v[154:157], v[18:21]
	v_mfma_f32_16x16x32_bf16 v[6:9], v[182:185], v[174:177], v[6:9]
	v_mfma_f32_16x16x32_bf16 v[2:5], v[190:193], v[174:177], v[2:5]
	v_mfma_f32_16x16x32_bf16 v[50:53], v[182:185], v[130:133], v[50:53]
	v_mfma_f32_16x16x32_bf16 v[54:57], v[190:193], v[130:133], v[54:57]
	s_add_i32 s72, 0, 0x18000
	v_add_u32_e32 v1, s72, v223
	s_barrier
	ds_read_b128 v[58:61], v1
	ds_read_b128 v[62:65], v1 offset:1024
	ds_read_b128 v[82:85], v1 offset:2048
	ds_read_b128 v[86:89], v1 offset:3072
	s_add_u32 s42, s42, s4
	s_addc_u32 s43, s43, 0
	s_mov_b32 m0, s81
	v_lshl_add_u64 v[134:135], s[42:43], 0, v[202:203]
	ds_read_b128 v[118:121], v230 offset:32768
	ds_read_b128 v[130:133], v230 offset:33792
	ds_read_b128 v[146:149], v230 offset:34816
	ds_read_b128 v[154:157], v230 offset:35840
	ds_read_b128 v[170:173], v230 offset:36864
	ds_read_b128 v[174:177], v230 offset:37888
	ds_read_b128 v[178:181], v230 offset:38912
	ds_read_b128 v[182:185], v230 offset:39936
	global_load_lds_dwordx4 v[134:135], off
	v_lshl_add_u64 v[134:135], s[42:43], 0, v[200:201]
	s_mov_b32 m0, s82
	s_nop 0
	global_load_lds_dwordx4 v[134:135], off
	s_waitcnt lgkmcnt(8)
	s_barrier
	s_waitcnt lgkmcnt(0)
	s_waitcnt lgkmcnt(0)
	v_mfma_f32_16x16x32_bf16 v[134:137], v[58:61], v[118:121], v[166:169]
	v_mfma_f32_16x16x32_bf16 v[166:169], v[62:65], v[130:133], v[134:137]
	v_mfma_f32_16x16x32_bf16 v[134:137], v[82:85], v[118:121], v[162:165]
	v_mfma_f32_16x16x32_bf16 v[162:165], v[86:89], v[130:133], v[134:137]
	v_mfma_f32_16x16x32_bf16 v[134:137], v[58:61], v[146:149], v[142:145]
	v_mfma_f32_16x16x32_bf16 v[142:145], v[62:65], v[154:157], v[134:137]
	v_mfma_f32_16x16x32_bf16 v[134:137], v[82:85], v[146:149], v[138:141]
	v_mfma_f32_16x16x32_bf16 v[126:129], v[58:61], v[170:173], v[126:129]
	v_mfma_f32_16x16x32_bf16 v[122:125], v[82:85], v[170:173], v[122:125]
	v_mfma_f32_16x16x32_bf16 v[110:113], v[58:61], v[178:181], v[110:113]
	v_mfma_f32_16x16x32_bf16 v[106:109], v[82:85], v[178:181], v[106:109]
	v_mfma_f32_16x16x32_bf16 v[138:141], v[86:89], v[154:157], v[134:137]
	v_mfma_f32_16x16x32_bf16 v[126:129], v[62:65], v[174:177], v[126:129]
	v_mfma_f32_16x16x32_bf16 v[122:125], v[86:89], v[174:177], v[122:125]
	v_mfma_f32_16x16x32_bf16 v[110:113], v[62:65], v[182:185], v[110:113]
	v_mfma_f32_16x16x32_bf16 v[106:109], v[86:89], v[182:185], v[106:109]
	s_barrier
	s_add_i32 s42, 0, 0x1c000
	s_add_i32 s43, s72, s78
	v_add_u32_e32 v1, s42, v223
	v_lshl_add_u64 v[134:135], v[214:215], 0, s[22:23]
	s_mov_b32 m0, s43
	ds_read_b128 v[186:189], v1
	ds_read_b128 v[190:193], v1 offset:1024
	ds_read_b128 v[208:211], v1 offset:2048
	ds_read_b128 v[232:235], v1 offset:3072
	global_load_lds_dwordx4 v[134:135], off
	v_lshl_add_u64 v[134:135], v[236:237], 0, s[22:23]
	s_add_i32 m0, s43, 0x2000
	s_nop 0
	global_load_lds_dwordx4 v[134:135], off
	s_barrier
	s_waitcnt lgkmcnt(0)
	s_waitcnt lgkmcnt(0)
	v_mfma_f32_16x16x32_bf16 v[66:69], v[208:211], v[118:121], v[66:69]
	v_mfma_f32_16x16x32_bf16 v[134:137], v[186:189], v[118:121], v[158:161]
	v_mfma_f32_16x16x32_bf16 v[150:153], v[232:235], v[130:133], v[66:69]
	v_mfma_f32_16x16x32_bf16 v[66:69], v[186:189], v[146:149], v[70:73]
	v_mfma_f32_16x16x32_bf16 v[158:161], v[190:193], v[130:133], v[134:137]
	v_mfma_f32_16x16x32_bf16 v[134:137], v[190:193], v[154:157], v[66:69]
	v_mfma_f32_16x16x32_bf16 v[66:69], v[208:211], v[146:149], v[74:77]
	v_mfma_f32_16x16x32_bf16 v[130:133], v[232:235], v[154:157], v[66:69]
	v_mfma_f32_16x16x32_bf16 v[66:69], v[186:189], v[170:173], v[78:81]
	v_mfma_f32_16x16x32_bf16 v[118:121], v[190:193], v[174:177], v[66:69]
	v_mfma_f32_16x16x32_bf16 v[66:69], v[208:211], v[170:173], v[114:117]
	v_mfma_f32_16x16x32_bf16 v[114:117], v[232:235], v[174:177], v[66:69]
	v_mfma_f32_16x16x32_bf16 v[66:69], v[186:189], v[178:181], v[102:105]
	v_mfma_f32_16x16x32_bf16 v[102:105], v[190:193], v[182:185], v[66:69]
	v_mfma_f32_16x16x32_bf16 v[66:69], v[208:211], v[178:181], v[98:101]
	v_mfma_f32_16x16x32_bf16 v[98:101], v[232:235], v[182:185], v[66:69]
	s_mov_b32 m0, s86
	v_lshl_add_u64 v[178:179], v[238:239], 0, s[22:23]
	s_barrier
	s_nop 2
	ds_read_b128 v[66:69], v230 offset:49152
	ds_read_b128 v[70:73], v230 offset:50176
	ds_read_b128 v[74:77], v230 offset:51200
	ds_read_b128 v[78:81], v230 offset:52224
	ds_read_b128 v[146:149], v230 offset:53248
	ds_read_b128 v[154:157], v230 offset:54272
	ds_read_b128 v[170:173], v230 offset:55296
	ds_read_b128 v[174:177], v230 offset:56320
	global_load_lds_dwordx4 v[178:179], off
	v_lshl_add_u64 v[178:179], v[240:241], 0, s[22:23]
	s_mov_b32 m0, s87
	s_nop 0
	global_load_lds_dwordx4 v[178:179], off
	s_barrier
	s_waitcnt lgkmcnt(0)
	s_waitcnt lgkmcnt(0)
	v_mfma_f32_16x16x32_bf16 v[94:97], v[58:61], v[66:69], v[94:97]
	v_mfma_f32_16x16x32_bf16 v[90:93], v[82:85], v[66:69], v[90:93]
	v_mfma_f32_16x16x32_bf16 v[46:49], v[58:61], v[74:77], v[46:49]
	v_mfma_f32_16x16x32_bf16 v[42:45], v[82:85], v[74:77], v[42:45]
	v_mfma_f32_16x16x32_bf16 v[30:33], v[58:61], v[146:149], v[30:33]
	v_mfma_f32_16x16x32_bf16 v[26:29], v[82:85], v[146:149], v[26:29]
	v_mfma_f32_16x16x32_bf16 v[14:17], v[58:61], v[170:173], v[14:17]
	v_mfma_f32_16x16x32_bf16 v[10:13], v[82:85], v[170:173], v[10:13]
	v_mfma_f32_16x16x32_bf16 v[94:97], v[62:65], v[70:73], v[94:97]
	v_mfma_f32_16x16x32_bf16 v[90:93], v[86:89], v[70:73], v[90:93]
	v_mfma_f32_16x16x32_bf16 v[46:49], v[62:65], v[78:81], v[46:49]
	v_mfma_f32_16x16x32_bf16 v[42:45], v[86:89], v[78:81], v[42:45]
	v_mfma_f32_16x16x32_bf16 v[30:33], v[62:65], v[154:157], v[30:33]
	v_mfma_f32_16x16x32_bf16 v[26:29], v[86:89], v[154:157], v[26:29]
	v_mfma_f32_16x16x32_bf16 v[14:17], v[62:65], v[174:177], v[14:17]
	v_mfma_f32_16x16x32_bf16 v[10:13], v[86:89], v[174:177], v[10:13]
	s_barrier
	s_add_i32 s42, s42, s78
	v_lshl_add_u64 v[58:59], v[242:243], 0, s[22:23]
	s_mov_b32 m0, s42
	s_nop 0
	global_load_lds_dwordx4 v[58:59], off
	v_lshl_add_u64 v[58:59], v[244:245], 0, s[22:23]
	s_add_i32 m0, s42, 0x2000
	s_nop 0
	global_load_lds_dwordx4 v[58:59], off
	s_waitcnt vmcnt(6)
	s_barrier
	v_mfma_f32_16x16x32_bf16 v[50:53], v[186:189], v[66:69], v[50:53]
	v_mfma_f32_16x16x32_bf16 v[86:89], v[190:193], v[70:73], v[50:53]
	v_mfma_f32_16x16x32_bf16 v[50:53], v[208:211], v[66:69], v[54:57]
	v_mfma_f32_16x16x32_bf16 v[38:41], v[186:189], v[74:77], v[38:41]
	v_mfma_f32_16x16x32_bf16 v[34:37], v[208:211], v[74:77], v[34:37]
	v_mfma_f32_16x16x32_bf16 v[22:25], v[186:189], v[146:149], v[22:25]
	v_mfma_f32_16x16x32_bf16 v[18:21], v[208:211], v[146:149], v[18:21]
	v_mfma_f32_16x16x32_bf16 v[6:9], v[186:189], v[170:173], v[6:9]
	v_mfma_f32_16x16x32_bf16 v[2:5], v[208:211], v[170:173], v[2:5]
	v_mfma_f32_16x16x32_bf16 v[82:85], v[232:235], v[70:73], v[50:53]
	v_mfma_f32_16x16x32_bf16 v[38:41], v[190:193], v[78:81], v[38:41]
	v_mfma_f32_16x16x32_bf16 v[34:37], v[232:235], v[78:81], v[34:37]
	v_mfma_f32_16x16x32_bf16 v[22:25], v[190:193], v[154:157], v[22:25]
	v_mfma_f32_16x16x32_bf16 v[18:21], v[232:235], v[154:157], v[18:21]
	v_mfma_f32_16x16x32_bf16 v[6:9], v[190:193], v[174:177], v[6:9]
	v_mfma_f32_16x16x32_bf16 v[2:5], v[232:235], v[174:177], v[2:5]
	s_add_u32 s27, s27, 0x100
	s_addc_u32 s91, s91, 0
	s_add_u32 s36, s36, 0x100
	s_addc_u32 s37, s37, 0
	s_cmp_ge_u32 s92, s32
	s_mov_b32 s42, s92
	s_barrier
	s_cbranch_scc0 .LBB0_1179
	s_cmp_eq_u32 s32, s84
	s_cbranch_scc1 .Ltail_done_1
	s_lshl_b32 s32, s3, 8
	s_add_i32 s32, s32, s85
	v_or_b32_e32 v249, s32, v221
	v_lshlrev_b32_e32 v249, 11, v249
	v_lshl_or_b32 v248, s38, 8, v224
	v_lshl_add_u32 v249, v248, 1, v249
	s_add_i32 s92, s42, 2
	s_add_u32 s72, s36, 0x80
	s_addc_u32 s43, s37, 0
	s_add_i32 s93, 0, 0x10000
	v_add_u32_e32 v1, s93, v223
	ds_read_b128 v[50:53], v1
	ds_read_b128 v[54:57], v1 offset:1024
	ds_read_b128 v[58:61], v1 offset:2048
	ds_read_b128 v[62:65], v1 offset:3072
	s_cmp_eq_u32 s88, s42
	s_cselect_b32 s42, s66, s72
	s_cselect_b32 s43, s67, s43
	s_cselect_b32 s73, s71, s91
	s_cselect_b32 s72, s70, s27
	v_lshl_add_u64 v[178:179], s[36:37], 0, v[206:207]
	s_add_i32 m0, s79, 0xc000
	ds_read_b128 v[66:69], v230
	ds_read_b128 v[70:73], v230 offset:1024
	ds_read_b128 v[74:77], v230 offset:2048
	ds_read_b128 v[78:81], v230 offset:3072
	ds_read_b128 v[146:149], v230 offset:4096
	ds_read_b128 v[154:157], v230 offset:5120
	ds_read_b128 v[170:173], v230 offset:6144
	ds_read_b128 v[174:177], v230 offset:7168
	global_load_lds_dwordx4 v[178:179], off
	v_lshl_add_u64 v[178:179], s[36:37], 0, v[204:205]
	s_add_i32 m0, s79, 0xe000
	s_nop 0
	global_load_lds_dwordx4 v[178:179], off
	s_waitcnt lgkmcnt(8)
	s_barrier
	s_waitcnt lgkmcnt(0)
	s_waitcnt lgkmcnt(0)
	v_mfma_f32_16x16x32_bf16 v[166:169], v[50:53], v[66:69], v[166:169]
	v_mfma_f32_16x16x32_bf16 v[162:165], v[58:61], v[66:69], v[162:165]
	v_mfma_f32_16x16x32_bf16 v[142:145], v[50:53], v[74:77], v[142:145]
	v_mfma_f32_16x16x32_bf16 v[138:141], v[58:61], v[74:77], v[138:141]
	v_mfma_f32_16x16x32_bf16 v[126:129], v[50:53], v[146:149], v[126:129]
	v_mfma_f32_16x16x32_bf16 v[122:125], v[58:61], v[146:149], v[122:125]
	v_mfma_f32_16x16x32_bf16 v[110:113], v[50:53], v[170:173], v[110:113]
	v_mfma_f32_16x16x32_bf16 v[106:109], v[58:61], v[170:173], v[106:109]
	v_mfma_f32_16x16x32_bf16 v[166:169], v[54:57], v[70:73], v[166:169]
	v_mfma_f32_16x16x32_bf16 v[162:165], v[62:65], v[70:73], v[162:165]
	v_mfma_f32_16x16x32_bf16 v[142:145], v[54:57], v[78:81], v[142:145]
	v_mfma_f32_16x16x32_bf16 v[138:141], v[62:65], v[78:81], v[138:141]
	v_mfma_f32_16x16x32_bf16 v[126:129], v[54:57], v[154:157], v[126:129]
	v_mfma_f32_16x16x32_bf16 v[122:125], v[62:65], v[154:157], v[122:125]
	v_mfma_f32_16x16x32_bf16 v[110:113], v[54:57], v[174:177], v[110:113]
	v_mfma_f32_16x16x32_bf16 v[106:109], v[62:65], v[174:177], v[106:109]
	s_barrier
	s_add_i32 s94, 0, 0x14000
	s_add_i32 s93, s93, s78
	v_add_u32_e32 v1, s94, v223
	v_lshl_add_u64 v[214:215], s[72:73], 0, v[202:203]
	s_mov_b32 m0, s93
	ds_read_b128 v[178:181], v1
	ds_read_b128 v[182:185], v1 offset:1024
	ds_read_b128 v[186:189], v1 offset:2048
	ds_read_b128 v[190:193], v1 offset:3072
	v_lshl_add_u64 v[236:237], s[72:73], 0, v[200:201]
	s_add_i32 m0, s93, 0x2000
	s_nop 0
	v_mov_b32_e32 v250, v249
	global_load_dword v251, v250, s[48:49]
	global_load_dword v251, v250, s[48:49] offset:256
	s_barrier
	s_waitcnt lgkmcnt(0)
	s_waitcnt lgkmcnt(0)
	v_mfma_f32_16x16x32_bf16 v[158:161], v[178:181], v[66:69], v[158:161]
	v_mfma_f32_16x16x32_bf16 v[66:69], v[186:189], v[66:69], v[150:153]
	v_mfma_f32_16x16x32_bf16 v[158:161], v[182:185], v[70:73], v[158:161]
	v_mfma_f32_16x16x32_bf16 v[66:69], v[190:193], v[70:73], v[66:69]
	v_mfma_f32_16x16x32_bf16 v[70:73], v[178:181], v[74:77], v[134:137]
	v_mfma_f32_16x16x32_bf16 v[74:77], v[186:189], v[74:77], v[130:133]
	v_mfma_f32_16x16x32_bf16 v[114:117], v[186:189], v[146:149], v[114:117]
	v_mfma_f32_16x16x32_bf16 v[102:105], v[178:181], v[170:173], v[102:105]
	v_mfma_f32_16x16x32_bf16 v[98:101], v[186:189], v[170:173], v[98:101]
	v_mfma_f32_16x16x32_bf16 v[70:73], v[182:185], v[78:81], v[70:73]
	v_mfma_f32_16x16x32_bf16 v[74:77], v[190:193], v[78:81], v[74:77]
	v_mfma_f32_16x16x32_bf16 v[78:81], v[178:181], v[146:149], v[118:121]
	v_mfma_f32_16x16x32_bf16 v[114:117], v[190:193], v[154:157], v[114:117]
	v_mfma_f32_16x16x32_bf16 v[102:105], v[182:185], v[174:177], v[102:105]
	v_mfma_f32_16x16x32_bf16 v[98:101], v[190:193], v[174:177], v[98:101]
	v_mfma_f32_16x16x32_bf16 v[78:81], v[182:185], v[154:157], v[78:81]
	s_mov_b32 m0, s79
	v_lshl_add_u64 v[238:239], s[42:43], 0, v[202:203]
	s_barrier
	ds_read_b128 v[118:121], v230 offset:16384
	ds_read_b128 v[130:133], v230 offset:17408
	ds_read_b128 v[134:137], v230 offset:18432
	ds_read_b128 v[146:149], v230 offset:19456
	ds_read_b128 v[150:153], v230 offset:20480
	ds_read_b128 v[154:157], v230 offset:21504
	ds_read_b128 v[170:173], v230 offset:22528
	ds_read_b128 v[174:177], v230 offset:23552
	v_lshl_add_u64 v[240:241], s[42:43], 0, v[200:201]
	s_mov_b32 m0, s80
	s_nop 0
	v_add_u32_e32 v250, 0x8000, v249
	global_load_dword v251, v250, s[48:49]
	global_load_dword v251, v250, s[48:49] offset:256
	s_barrier
	s_waitcnt lgkmcnt(0)
	s_waitcnt lgkmcnt(0)
	v_mfma_f32_16x16x32_bf16 v[94:97], v[50:53], v[118:121], v[94:97]
	v_mfma_f32_16x16x32_bf16 v[90:93], v[58:61], v[118:121], v[90:93]
	v_mfma_f32_16x16x32_bf16 v[46:49], v[50:53], v[134:137], v[46:49]
	v_mfma_f32_16x16x32_bf16 v[42:45], v[58:61], v[134:137], v[42:45]
	v_mfma_f32_16x16x32_bf16 v[30:33], v[50:53], v[150:153], v[30:33]
	v_mfma_f32_16x16x32_bf16 v[26:29], v[58:61], v[150:153], v[26:29]
	v_mfma_f32_16x16x32_bf16 v[14:17], v[50:53], v[170:173], v[14:17]
	v_mfma_f32_16x16x32_bf16 v[10:13], v[58:61], v[170:173], v[10:13]
	v_mfma_f32_16x16x32_bf16 v[94:97], v[54:57], v[130:133], v[94:97]
	v_mfma_f32_16x16x32_bf16 v[90:93], v[62:65], v[130:133], v[90:93]
	v_mfma_f32_16x16x32_bf16 v[46:49], v[54:57], v[146:149], v[46:49]
	v_mfma_f32_16x16x32_bf16 v[42:45], v[62:65], v[146:149], v[42:45]
	v_mfma_f32_16x16x32_bf16 v[30:33], v[54:57], v[154:157], v[30:33]
	v_mfma_f32_16x16x32_bf16 v[26:29], v[62:65], v[154:157], v[26:29]
	v_mfma_f32_16x16x32_bf16 v[14:17], v[54:57], v[174:177], v[14:17]
	v_mfma_f32_16x16x32_bf16 v[10:13], v[62:65], v[174:177], v[10:13]
	s_barrier
	s_add_u32 s72, s72, s4
	s_addc_u32 s73, s73, 0
	s_add_i32 s93, s94, s78
	v_lshl_add_u64 v[242:243], s[72:73], 0, v[202:203]
	s_mov_b32 m0, s93
	v_lshl_add_u64 v[244:245], s[72:73], 0, v[200:201]
	s_add_i32 m0, s93, 0x2000
	s_nop 0
	v_add_u32_e32 v250, 0x10000, v249
	global_load_dword v251, v250, s[48:49]
	global_load_dword v251, v250, s[48:49] offset:256
	s_waitcnt vmcnt(6)
	s_barrier
	v_mfma_f32_16x16x32_bf16 v[38:41], v[178:181], v[134:137], v[38:41]
	v_mfma_f32_16x16x32_bf16 v[34:37], v[186:189], v[134:137], v[34:37]
	v_mfma_f32_16x16x32_bf16 v[22:25], v[178:181], v[150:153], v[22:25]
	v_mfma_f32_16x16x32_bf16 v[18:21], v[186:189], v[150:153], v[18:21]
	v_mfma_f32_16x16x32_bf16 v[6:9], v[178:181], v[170:173], v[6:9]
	v_mfma_f32_16x16x32_bf16 v[2:5], v[186:189], v[170:173], v[2:5]
	v_mfma_f32_16x16x32_bf16 v[50:53], v[178:181], v[118:121], v[86:89]
	v_mfma_f32_16x16x32_bf16 v[54:57], v[186:189], v[118:121], v[82:85]
	v_mfma_f32_16x16x32_bf16 v[38:41], v[182:185], v[146:149], v[38:41]
	v_mfma_f32_16x16x32_bf16 v[34:37], v[190:193], v[146:149], v[34:37]
	v_mfma_f32_16x16x32_bf16 v[22:25], v[182:185], v[154:157], v[22:25]
	v_mfma_f32_16x16x32_bf16 v[18:21], v[190:193], v[154:157], v[18:21]
	v_mfma_f32_16x16x32_bf16 v[6:9], v[182:185], v[174:177], v[6:9]
	v_mfma_f32_16x16x32_bf16 v[2:5], v[190:193], v[174:177], v[2:5]
	v_mfma_f32_16x16x32_bf16 v[50:53], v[182:185], v[130:133], v[50:53]
	v_mfma_f32_16x16x32_bf16 v[54:57], v[190:193], v[130:133], v[54:57]
	s_add_i32 s72, 0, 0x18000
	v_add_u32_e32 v1, s72, v223
	s_barrier
	ds_read_b128 v[58:61], v1
	ds_read_b128 v[62:65], v1 offset:1024
	ds_read_b128 v[82:85], v1 offset:2048
	ds_read_b128 v[86:89], v1 offset:3072
	s_add_u32 s42, s42, s4
	s_addc_u32 s43, s43, 0
	s_mov_b32 m0, s81
	v_lshl_add_u64 v[134:135], s[42:43], 0, v[202:203]
	ds_read_b128 v[118:121], v230 offset:32768
	ds_read_b128 v[130:133], v230 offset:33792
	ds_read_b128 v[146:149], v230 offset:34816
	ds_read_b128 v[154:157], v230 offset:35840
	ds_read_b128 v[170:173], v230 offset:36864
	ds_read_b128 v[174:177], v230 offset:37888
	ds_read_b128 v[178:181], v230 offset:38912
	ds_read_b128 v[182:185], v230 offset:39936
	v_lshl_add_u64 v[134:135], s[42:43], 0, v[200:201]
	s_mov_b32 m0, s82
	s_nop 0
	s_waitcnt lgkmcnt(8)
	v_add_u32_e32 v250, 0x18000, v249
	global_load_dword v251, v250, s[48:49]
	global_load_dword v251, v250, s[48:49] offset:256
	s_barrier
	s_waitcnt lgkmcnt(0)
	s_waitcnt lgkmcnt(0)
	v_mfma_f32_16x16x32_bf16 v[134:137], v[58:61], v[118:121], v[166:169]
	v_mfma_f32_16x16x32_bf16 v[166:169], v[62:65], v[130:133], v[134:137]
	v_mfma_f32_16x16x32_bf16 v[134:137], v[82:85], v[118:121], v[162:165]
	v_mfma_f32_16x16x32_bf16 v[162:165], v[86:89], v[130:133], v[134:137]
	v_mfma_f32_16x16x32_bf16 v[134:137], v[58:61], v[146:149], v[142:145]
	v_mfma_f32_16x16x32_bf16 v[142:145], v[62:65], v[154:157], v[134:137]
	v_mfma_f32_16x16x32_bf16 v[134:137], v[82:85], v[146:149], v[138:141]
	v_mfma_f32_16x16x32_bf16 v[126:129], v[58:61], v[170:173], v[126:129]
	v_mfma_f32_16x16x32_bf16 v[122:125], v[82:85], v[170:173], v[122:125]
	v_mfma_f32_16x16x32_bf16 v[110:113], v[58:61], v[178:181], v[110:113]
	v_mfma_f32_16x16x32_bf16 v[106:109], v[82:85], v[178:181], v[106:109]
	v_mfma_f32_16x16x32_bf16 v[138:141], v[86:89], v[154:157], v[134:137]
	v_mfma_f32_16x16x32_bf16 v[126:129], v[62:65], v[174:177], v[126:129]
	v_mfma_f32_16x16x32_bf16 v[122:125], v[86:89], v[174:177], v[122:125]
	v_mfma_f32_16x16x32_bf16 v[110:113], v[62:65], v[182:185], v[110:113]
	v_mfma_f32_16x16x32_bf16 v[106:109], v[86:89], v[182:185], v[106:109]
	s_barrier
	s_add_i32 s42, 0, 0x1c000
	s_add_i32 s43, s72, s78
	v_add_u32_e32 v1, s42, v223
	v_lshl_add_u64 v[134:135], v[214:215], 0, s[22:23]
	s_mov_b32 m0, s43
	ds_read_b128 v[186:189], v1
	ds_read_b128 v[190:193], v1 offset:1024
	ds_read_b128 v[208:211], v1 offset:2048
	ds_read_b128 v[232:235], v1 offset:3072
	v_lshl_add_u64 v[134:135], v[236:237], 0, s[22:23]
	s_add_i32 m0, s43, 0x2000
	s_nop 0
	v_add_u32_e32 v250, 0x40000, v249
	global_load_dword v251, v250, s[48:49]
	global_load_dword v251, v250, s[48:49] offset:256
	s_barrier
	s_waitcnt lgkmcnt(0)
	s_waitcnt lgkmcnt(0)
	v_mfma_f32_16x16x32_bf16 v[66:69], v[208:211], v[118:121], v[66:69]
	v_mfma_f32_16x16x32_bf16 v[134:137], v[186:189], v[118:121], v[158:161]
	v_mfma_f32_16x16x32_bf16 v[150:153], v[232:235], v[130:133], v[66:69]
	v_mfma_f32_16x16x32_bf16 v[66:69], v[186:189], v[146:149], v[70:73]
	v_mfma_f32_16x16x32_bf16 v[158:161], v[190:193], v[130:133], v[134:137]
	v_mfma_f32_16x16x32_bf16 v[134:137], v[190:193], v[154:157], v[66:69]
	v_mfma_f32_16x16x32_bf16 v[66:69], v[208:211], v[146:149], v[74:77]
	v_mfma_f32_16x16x32_bf16 v[130:133], v[232:235], v[154:157], v[66:69]
	v_mfma_f32_16x16x32_bf16 v[66:69], v[186:189], v[170:173], v[78:81]
	v_mfma_f32_16x16x32_bf16 v[118:121], v[190:193], v[174:177], v[66:69]
	v_mfma_f32_16x16x32_bf16 v[66:69], v[208:211], v[170:173], v[114:117]
	v_mfma_f32_16x16x32_bf16 v[114:117], v[232:235], v[174:177], v[66:69]
	v_mfma_f32_16x16x32_bf16 v[66:69], v[186:189], v[178:181], v[102:105]
	v_mfma_f32_16x16x32_bf16 v[102:105], v[190:193], v[182:185], v[66:69]
	v_mfma_f32_16x16x32_bf16 v[66:69], v[208:211], v[178:181], v[98:101]
	v_mfma_f32_16x16x32_bf16 v[98:101], v[232:235], v[182:185], v[66:69]
	s_mov_b32 m0, s86
	v_lshl_add_u64 v[178:179], v[238:239], 0, s[22:23]
	s_barrier
	s_nop 2
	ds_read_b128 v[66:69], v230 offset:49152
	ds_read_b128 v[70:73], v230 offset:50176
	ds_read_b128 v[74:77], v230 offset:51200
	ds_read_b128 v[78:81], v230 offset:52224
	ds_read_b128 v[146:149], v230 offset:53248
	ds_read_b128 v[154:157], v230 offset:54272
	ds_read_b128 v[170:173], v230 offset:55296
	ds_read_b128 v[174:177], v230 offset:56320
	v_lshl_add_u64 v[178:179], v[240:241], 0, s[22:23]
	s_mov_b32 m0, s87
	s_nop 0
	v_add_u32_e32 v250, 0x48000, v249
	global_load_dword v251, v250, s[48:49]
	global_load_dword v251, v250, s[48:49] offset:256
	s_barrier
	s_waitcnt lgkmcnt(0)
	s_waitcnt lgkmcnt(0)
	v_mfma_f32_16x16x32_bf16 v[94:97], v[58:61], v[66:69], v[94:97]
	v_mfma_f32_16x16x32_bf16 v[90:93], v[82:85], v[66:69], v[90:93]
	v_mfma_f32_16x16x32_bf16 v[46:49], v[58:61], v[74:77], v[46:49]
	v_mfma_f32_16x16x32_bf16 v[42:45], v[82:85], v[74:77], v[42:45]
	v_mfma_f32_16x16x32_bf16 v[30:33], v[58:61], v[146:149], v[30:33]
	v_mfma_f32_16x16x32_bf16 v[26:29], v[82:85], v[146:149], v[26:29]
	v_mfma_f32_16x16x32_bf16 v[14:17], v[58:61], v[170:173], v[14:17]
	v_mfma_f32_16x16x32_bf16 v[10:13], v[82:85], v[170:173], v[10:13]
	v_mfma_f32_16x16x32_bf16 v[94:97], v[62:65], v[70:73], v[94:97]
	v_mfma_f32_16x16x32_bf16 v[90:93], v[86:89], v[70:73], v[90:93]
	v_mfma_f32_16x16x32_bf16 v[46:49], v[62:65], v[78:81], v[46:49]
	v_mfma_f32_16x16x32_bf16 v[42:45], v[86:89], v[78:81], v[42:45]
	v_mfma_f32_16x16x32_bf16 v[30:33], v[62:65], v[154:157], v[30:33]
	v_mfma_f32_16x16x32_bf16 v[26:29], v[86:89], v[154:157], v[26:29]
	v_mfma_f32_16x16x32_bf16 v[14:17], v[62:65], v[174:177], v[14:17]
	v_mfma_f32_16x16x32_bf16 v[10:13], v[86:89], v[174:177], v[10:13]
	s_barrier
	s_add_i32 s42, s42, s78
	v_lshl_add_u64 v[58:59], v[242:243], 0, s[22:23]
	s_mov_b32 m0, s42
	s_nop 0
	v_lshl_add_u64 v[58:59], v[244:245], 0, s[22:23]
	s_add_i32 m0, s42, 0x2000
	s_nop 0
	v_add_u32_e32 v250, 0x50000, v249
	global_load_dword v251, v250, s[48:49]
	global_load_dword v251, v250, s[48:49] offset:256
	v_add_u32_e32 v250, 0x58000, v249
	global_load_dword v251, v250, s[48:49]
	global_load_dword v251, v250, s[48:49] offset:256
	s_barrier
	v_mfma_f32_16x16x32_bf16 v[50:53], v[186:189], v[66:69], v[50:53]
	v_mfma_f32_16x16x32_bf16 v[86:89], v[190:193], v[70:73], v[50:53]
	v_mfma_f32_16x16x32_bf16 v[50:53], v[208:211], v[66:69], v[54:57]
	v_mfma_f32_16x16x32_bf16 v[38:41], v[186:189], v[74:77], v[38:41]
	v_mfma_f32_16x16x32_bf16 v[34:37], v[208:211], v[74:77], v[34:37]
	v_mfma_f32_16x16x32_bf16 v[22:25], v[186:189], v[146:149], v[22:25]
	v_mfma_f32_16x16x32_bf16 v[18:21], v[208:211], v[146:149], v[18:21]
	v_mfma_f32_16x16x32_bf16 v[6:9], v[186:189], v[170:173], v[6:9]
	v_mfma_f32_16x16x32_bf16 v[2:5], v[208:211], v[170:173], v[2:5]
	v_mfma_f32_16x16x32_bf16 v[82:85], v[232:235], v[70:73], v[50:53]
	v_mfma_f32_16x16x32_bf16 v[38:41], v[190:193], v[78:81], v[38:41]
	v_mfma_f32_16x16x32_bf16 v[34:37], v[232:235], v[78:81], v[34:37]
	v_mfma_f32_16x16x32_bf16 v[22:25], v[190:193], v[154:157], v[22:25]
	v_mfma_f32_16x16x32_bf16 v[18:21], v[232:235], v[154:157], v[18:21]
	v_mfma_f32_16x16x32_bf16 v[6:9], v[190:193], v[174:177], v[6:9]
	v_mfma_f32_16x16x32_bf16 v[2:5], v[232:235], v[174:177], v[2:5]
	s_add_u32 s27, s27, 0x100
	s_addc_u32 s91, s91, 0
	s_add_u32 s36, s36, 0x100
	s_addc_u32 s37, s37, 0
	s_cmp_ge_u32 s92, s84
	s_mov_b32 s42, s92
	s_barrier

.LBB0_1229:
	s_lshl_b32 s29, s36, 4
	s_and_b32 s37, s29, 0xffffffc0
	v_or_b32_e32 v100, s37, v135
	v_ashrrev_i32_e32 v101, 31, v100
	v_lshlrev_b64 v[102:103], 11, v[42:43]
	v_lshlrev_b64 v[38:39], 2, v[100:101]
	v_lshl_add_u64 v[42:43], s[48:49], 0, v[102:103]
	v_lshl_add_u64 v[34:35], s[52:53], 0, v[38:39]
	v_lshl_add_u64 v[38:39], s[54:55], 0, v[38:39]
	v_lshl_add_u64 v[42:43], v[100:101], 1, v[42:43]
	flat_load_dwordx4 v[34:37], v[34:35]
	v_or_b32_e32 v2, s28, v1
	flat_load_dwordx4 v[38:41], v[38:39]
	v_mul_u32_u24_e32 v2, s75, v2
	flat_load_dwordx2 v[120:121], v[42:43]
	v_or_b32_e32 v42, s37, v136
	v_ashrrev_i32_e32 v43, 31, v42
	v_or_b32_e32 v4, s37, v1
	v_lshl_add_u64 v[44:45], v[42:43], 1, 32
	v_mad_i64_i32 v[124:125], s[28:29], s27, v42, v[76:77]
	v_lshl_or_b32 v8, v4, 1, 32
	v_lshlrev_b32_e32 v42, 1, v2
	v_mov_b32_e32 v43, v0
	v_mad_u64_u32 v[122:123], s[28:29], s75, v44, v[76:77]
	v_ashrrev_i32_e32 v6, 31, v4
	v_mad_u64_u32 v[126:127], s[28:29], s75, v8, v[76:77]
	v_mad_i64_i32 v[128:129], s[28:29], s27, v4, v[76:77]
	v_lshl_add_u64 v[130:131], v[78:79], 0, v[42:43]
	v_lshl_add_u64 v[132:133], v[80:81], 0, v[42:43]
	v_mov_b32_e32 v42, 0
	v_mad_i32_i24 v123, s75, v45, v123
	v_mad_i32_i24 v127, s75, v6, v127
	s_mov_b32 s28, 0
	v_mov_b32_e32 v43, v42
	v_mov_b32_e32 v44, v42
	v_mov_b32_e32 v45, v42
	v_mov_b32_e32 v46, v42
	v_mov_b32_e32 v47, v42
	v_mov_b32_e32 v48, v42
	v_mov_b32_e32 v49, v42
	v_mov_b32_e32 v50, v42
	v_mov_b32_e32 v51, v42
	v_mov_b32_e32 v52, v42
	v_mov_b32_e32 v53, v42
	v_mov_b32_e32 v54, v42
	v_mov_b32_e32 v55, v42
	v_mov_b32_e32 v56, v42
	v_mov_b32_e32 v57, v42
	v_mov_b32_e32 v58, v42
	v_mov_b32_e32 v59, v42
	v_mov_b32_e32 v60, v42
	v_mov_b32_e32 v61, v42
	v_mov_b32_e32 v62, v42
	v_mov_b32_e32 v63, v42
	v_mov_b32_e32 v64, v42
	v_mov_b32_e32 v65, v42
	v_mov_b32_e32 v66, v42
	v_mov_b32_e32 v67, v42
	v_mov_b32_e32 v68, v42
	v_mov_b32_e32 v69, v42
	v_mov_b32_e32 v70, v42
	v_mov_b32_e32 v71, v42
	v_mov_b32_e32 v72, v42
	v_mov_b32_e32 v73, v42
	v_lshl_add_u64 v[122:123], v[122:123], 0, v[74:75]
	v_lshl_add_u64 v[124:125], v[124:125], 0, v[74:75]
	v_lshl_add_u64 v[126:127], v[126:127], 0, v[74:75]
	v_lshl_add_u64 v[128:129], v[128:129], 0, v[74:75]
	v_lshl_add_u64 v[130:131], v[130:131], 0, v[74:75]
	v_lshl_add_u64 v[132:133], v[132:133], 0, v[74:75]
	s_mov_b64 s[100:101], 0xc0
	s_lshl_b32 s98, s3, 1
	s_mov_b32 s99, 0
	v_mov_b32_e32 v251, 0
.Lsg1_touch:
	v_mov_b32_e32 v250, s99
	v_lshl_add_u64 v[248:249], v[128:129], 0, v[250:251]
	global_load_dword v247, v[248:249], off
	v_lshl_add_u64 v[248:249], v[132:133], 0, v[250:251]
	global_load_dword v247, v[248:249], off
	v_lshl_add_u64 v[248:249], v[126:127], 0, v[250:251]
	global_load_dword v247, v[248:249], off
	v_lshl_add_u64 v[248:249], v[130:131], 0, v[250:251]
	global_load_dword v247, v[248:249], off
	v_lshl_add_u64 v[248:249], v[124:125], 0, v[250:251]
	global_load_dword v247, v[248:249], off
	v_lshl_add_u64 v[248:249], v[122:123], 0, v[250:251]
	global_load_dword v247, v[248:249], off
	s_addk_i32 s99, 0x80
	s_cmp_lt_u32 s99, s98
	s_cbranch_scc1 .Lsg1_touch
